# P5 epilogue first row pair: counted waits (row A + gain loads first, row B loads waited at their first use past row A's stores)
# speedup vs baseline: 1.0006x; 1.0006x over previous
.LBB0_1265:
	s_cmp_gt_i32 s17, 63
	v_add_u32_e32 v130, 0xffffc000, v174
	s_cselect_b64 vcc, -1, 0
	v_cndmask_b32_e32 v130, v174, v130, vcc
	v_readlane_b32 s36, v245, 0
	s_and_b64 s[10:11], vcc, exec
	v_readlane_b32 s37, v245, 1
	v_readlane_b32 s38, v245, 2
	v_readlane_b32 s39, v245, 3
	v_ashrrev_i32_e32 v131, 31, v130
	v_readlane_b32 s40, v245, 4
	v_readlane_b32 s41, v245, 5
	v_readlane_b32 s42, v245, 6
	v_readlane_b32 s43, v245, 7
	v_readlane_b32 s44, v245, 8
	v_readlane_b32 s45, v245, 9
	v_readlane_b32 s46, v245, 10
	v_readlane_b32 s47, v245, 11
	v_readlane_b32 s48, v245, 12
	v_readlane_b32 s49, v245, 13
	v_readlane_b32 s50, v245, 14
	v_readlane_b32 s51, v245, 15
	s_cselect_b32 s73, s39, s37
	s_cselect_b32 s72, s38, s36
	v_lshlrev_b64 v[130:131], 12, v[130:131]
	v_lshlrev_b64 v[176:177], 2, v[172:173]
	v_lshl_add_u64 v[130:131], s[72:73], 0, v[130:131]
	v_readlane_b32 s36, v245, 19
	v_lshl_add_u64 v[130:131], v[130:131], 0, v[176:177]
	v_readlane_b32 s38, v245, 21
	v_readlane_b32 s39, v245, 22
	global_load_dwordx4 v[188:191], v[130:131], off
	global_load_dwordx4 v[192:195], v[130:131], off offset:64
	global_load_dwordx4 v[196:199], v[130:131], off offset:512
	global_load_dwordx4 v[200:203], v[130:131], off offset:576
	v_lshl_add_u64 v[130:131], s[38:39], 0, v[176:177]
	global_load_dwordx4 v[142:145], v[130:131], off
	global_load_dwordx4 v[138:141], v[130:131], off offset:64
	global_load_dwordx4 v[134:137], v[130:131], off offset:512
	v_or_b32_e32 v166, 16, v174
	v_add_u32_e32 v146, 0xffffc010, v174
	v_cndmask_b32_e32 v146, v166, v146, vcc
	v_ashrrev_i32_e32 v147, 31, v146
	v_lshlrev_b64 v[146:147], 12, v[146:147]
	v_lshl_add_u64 v[146:147], s[72:73], 0, v[146:147]
	v_lshl_add_u64 v[146:147], v[146:147], 0, v[176:177]
	global_load_dwordx4 v[130:133], v[130:131], off offset:576
	s_nop 0
	global_load_dwordx4 v[158:161], v[146:147], off
	global_load_dwordx4 v[154:157], v[146:147], off offset:64
	global_load_dwordx4 v[150:153], v[146:147], off offset:512
	s_nop 0
	global_load_dwordx4 v[146:149], v[146:147], off offset:576
	v_and_b32_e32 v178, 64, v185
	v_xor_b32_e32 v204, 16, v185
	v_add_u32_e32 v206, 64, v178
	v_xor_b32_e32 v205, 32, v185
	v_mov_b32_e32 v175, v167
	v_cmp_lt_i32_e64 s[10:11], v204, v206
	v_lshlrev_b64 v[178:179], 12, v[174:175]
	v_lshlrev_b64 v[186:187], 11, v[174:175]
	v_cndmask_b32_e64 v207, v185, v204, s[10:11]
	v_cmp_lt_i32_e64 s[10:11], v205, v206
	v_lshl_add_u64 v[178:179], s[20:21], 0, v[178:179]
	v_lshl_add_u64 v[178:179], v[178:179], 0, v[176:177]
	v_cndmask_b32_e64 v206, v185, v205, s[10:11]
	v_lshl_add_u64 v[204:205], s[22:23], 0, v[186:187]
	v_lshlrev_b32_e32 v187, 2, v207
	v_lshlrev_b32_e32 v186, 2, v206
	v_lshl_add_u64 v[204:205], v[172:173], 1, v[204:205]
	v_readlane_b32 s37, v245, 20
	v_readlane_b32 s40, v245, 23
	v_readlane_b32 s41, v245, 24
	v_readlane_b32 s42, v245, 25
	v_readlane_b32 s43, v245, 26
	v_readlane_b32 s44, v245, 27
	v_readlane_b32 s45, v245, 28
	v_readlane_b32 s46, v245, 29
	v_readlane_b32 s47, v245, 30
	v_readlane_b32 s48, v245, 31
	v_readlane_b32 s49, v245, 32
	v_readlane_b32 s50, v245, 33
	v_readlane_b32 s51, v245, 34
	s_waitcnt vmcnt(4)
	v_pk_add_f32 v[190:191], v[128:129], v[190:191]
	v_pk_add_f32 v[188:189], v[126:127], v[188:189]
	v_pk_add_f32 v[194:195], v[124:125], v[194:195]
	v_pk_add_f32 v[192:193], v[122:123], v[192:193]
	v_pk_add_f32 v[198:199], v[120:121], v[198:199]
	v_pk_add_f32 v[196:197], v[118:119], v[196:197]
	v_mul_f32_e32 v218, v189, v189
	v_mul_f32_e32 v219, v191, v191
	v_pk_mul_f32 v[206:207], v[144:145], v[190:191]
	v_pk_mul_f32 v[208:209], v[142:143], v[188:189]
	v_mul_f32_e32 v220, v193, v193
	v_mul_f32_e32 v221, v195, v195
	global_store_dwordx4 v[178:179], v[188:191], off
	v_mul_f32_e32 v222, v197, v197
	v_mul_f32_e32 v223, v199, v199
	v_fmac_f32_e32 v218, v188, v188
	v_fmac_f32_e32 v219, v190, v190
	v_cvt_pk_bf16_f32 v188, v208, v209
	v_cvt_pk_bf16_f32 v189, v206, v207
	v_fmac_f32_e32 v220, v192, v192
	v_fmac_f32_e32 v221, v194, v194
	v_fmac_f32_e32 v222, v196, v196
	v_fmac_f32_e32 v223, v198, v198
	v_add_f32_e32 v207, v218, v219
	global_store_dwordx2 v[204:205], v[188:189], off
	global_store_dwordx4 v[178:179], v[192:195], off offset:64
	v_add_f32_e32 v188, v220, v221
	v_pk_add_f32 v[202:203], v[116:117], v[202:203]
	v_pk_add_f32 v[200:201], v[114:115], v[200:201]
	v_add_f32_e32 v189, v222, v223
	v_add_f32_e32 v188, v207, v188
	v_mul_f32_e32 v224, v201, v201
	v_add_f32_e32 v188, v188, v189
	v_mul_f32_e32 v189, v203, v203
	v_pk_mul_f32 v[210:211], v[140:141], v[194:195]
	v_pk_mul_f32 v[212:213], v[138:139], v[192:193]
	v_fmac_f32_e32 v224, v200, v200
	v_fmac_f32_e32 v189, v202, v202
	v_cvt_pk_bf16_f32 v190, v212, v213
	v_cvt_pk_bf16_f32 v191, v210, v211
	v_add_f32_e32 v189, v224, v189
	global_store_dwordx2 v[204:205], v[190:191], off offset:32
	global_store_dwordx4 v[178:179], v[196:199], off offset:512
	v_add_f32_e32 v190, v188, v189
	ds_bpermute_b32 v191, v187, v190
	v_pk_mul_f32 v[214:215], v[136:137], v[198:199]
	v_pk_mul_f32 v[216:217], v[134:135], v[196:197]
	v_cvt_pk_bf16_f32 v207, v214, v215
	v_cvt_pk_bf16_f32 v206, v216, v217
	global_store_dwordx2 v[204:205], v[206:207], off offset:256
	global_store_dwordx4 v[178:179], v[200:203], off offset:576
	s_waitcnt lgkmcnt(0)
	v_add_f32_e32 v178, v190, v191
	ds_bpermute_b32 v179, v186, v178
	v_pk_mul_f32 v[188:189], v[132:133], v[202:203]
	v_pk_mul_f32 v[190:191], v[130:131], v[200:201]
	s_nop 0
	v_cvt_pk_bf16_f32 v190, v190, v191
	v_cvt_pk_bf16_f32 v191, v188, v189
	global_store_dwordx2 v[204:205], v[190:191], off offset:288
	s_and_saveexec_b64 s[10:11], s[8:9]
	s_cbranch_execz .LBB0_1267
	s_waitcnt lgkmcnt(0)
	v_add_f32_e32 v188, v178, v179
	s_lshl_b32 s38, s26, 2
	v_lshlrev_b64 v[178:179], 6, v[174:175]
	s_ashr_i32 s39, s38, 31
	v_lshl_add_u64 v[178:179], s[24:25], 0, v[178:179]
	v_lshl_add_u64 v[178:179], s[38:39], 2, v[178:179]
	s_lshl_b32 s38, s55, 2
	s_mov_b32 s39, s15
	v_lshl_add_u64 v[178:179], v[178:179], 0, s[38:39]
	global_store_dword v[178:179], v188, off
.LBB0_1267:
	s_or_b64 exec, exec, s[10:11]
	s_waitcnt lgkmcnt(0)
	v_lshlrev_b64 v[178:179], 12, v[166:167]
	v_lshl_add_u64 v[178:179], s[20:21], 0, v[178:179]
	s_waitcnt vmcnt(8)
	v_pk_add_f32 v[160:161], v[112:113], v[160:161]
	v_pk_add_f32 v[158:159], v[110:111], v[158:159]
	v_lshl_add_u64 v[178:179], v[172:173], 2, v[178:179]
	v_lshlrev_b64 v[188:189], 11, v[166:167]
	v_mul_f32_e32 v175, v159, v159
	v_mul_f32_e32 v190, v161, v161
	v_lshl_add_u64 v[188:189], s[22:23], 0, v[188:189]
	global_store_dwordx4 v[178:179], v[158:161], off
	v_fmac_f32_e32 v175, v158, v158
	v_fmac_f32_e32 v190, v160, v160
	v_pk_mul_f32 v[160:161], v[144:145], v[160:161]
	v_pk_mul_f32 v[158:159], v[142:143], v[158:159]
	v_lshl_add_u64 v[188:189], v[172:173], 1, v[188:189]
	v_cvt_pk_bf16_f32 v158, v158, v159
	v_cvt_pk_bf16_f32 v159, v160, v161
	v_pk_add_f32 v[156:157], v[108:109], v[156:157]
	v_pk_add_f32 v[154:155], v[106:107], v[154:155]
	global_store_dwordx2 v[188:189], v[158:159], off
	v_mul_f32_e32 v158, v155, v155
	v_mul_f32_e32 v159, v157, v157
	global_store_dwordx4 v[178:179], v[154:157], off offset:64
	v_fmac_f32_e32 v158, v154, v154
	v_fmac_f32_e32 v159, v156, v156
	v_pk_mul_f32 v[156:157], v[140:141], v[156:157]
	v_pk_mul_f32 v[154:155], v[138:139], v[154:155]
	v_pk_add_f32 v[152:153], v[104:105], v[152:153]
	v_cvt_pk_bf16_f32 v154, v154, v155
	v_cvt_pk_bf16_f32 v155, v156, v157
	v_pk_add_f32 v[150:151], v[102:103], v[150:151]
	global_store_dwordx2 v[188:189], v[154:155], off offset:32
	v_mul_f32_e32 v154, v151, v151
	v_mul_f32_e32 v155, v153, v153
	v_add_f32_e32 v175, v175, v190
	v_add_f32_e32 v158, v158, v159
	v_fmac_f32_e32 v154, v150, v150
	v_fmac_f32_e32 v155, v152, v152
	v_add_f32_e32 v158, v175, v158
	global_store_dwordx4 v[178:179], v[150:153], off offset:512
	v_add_f32_e32 v154, v154, v155
	v_add_f32_e32 v155, v158, v154
	v_pk_mul_f32 v[150:151], v[134:135], v[150:151]
	v_pk_mul_f32 v[152:153], v[136:137], v[152:153]
	v_cvt_pk_bf16_f32 v154, v150, v151
	v_pk_add_f32 v[150:151], v[100:101], v[148:149]
	v_pk_add_f32 v[148:149], v[98:99], v[146:147]
	v_mul_f32_e32 v147, v151, v151
	v_mul_f32_e32 v146, v149, v149
	v_fmac_f32_e32 v146, v148, v148
	v_fmac_f32_e32 v147, v150, v150
	v_add_f32_e32 v146, v146, v147
	v_add_f32_e32 v146, v155, v146
	ds_bpermute_b32 v147, v187, v146
	v_cvt_pk_bf16_f32 v155, v152, v153
	global_store_dwordx2 v[188:189], v[154:155], off offset:256
	global_store_dwordx4 v[178:179], v[148:151], off offset:576
	s_waitcnt lgkmcnt(0)
	v_add_f32_e32 v146, v146, v147
	ds_bpermute_b32 v147, v186, v146
	v_pk_mul_f32 v[150:151], v[132:133], v[150:151]
	v_pk_mul_f32 v[148:149], v[130:131], v[148:149]
	s_nop 0
	v_cvt_pk_bf16_f32 v148, v148, v149
	v_cvt_pk_bf16_f32 v149, v150, v151
	global_store_dwordx2 v[188:189], v[148:149], off offset:288
	s_and_saveexec_b64 s[10:11], s[8:9]
	s_cbranch_execz .LBB0_1269
	s_waitcnt lgkmcnt(0)
	v_add_f32_e32 v148, v146, v147
	s_lshl_b32 s38, s26, 2
	v_lshlrev_b64 v[146:147], 6, v[166:167]
	s_ashr_i32 s39, s38, 31
	v_lshl_add_u64 v[146:147], s[24:25], 0, v[146:147]
	v_lshl_add_u64 v[146:147], s[38:39], 2, v[146:147]
	s_lshl_b32 s38, s55, 2
	s_mov_b32 s39, s15
	v_lshl_add_u64 v[146:147], v[146:147], 0, s[38:39]
	global_store_dword v[146:147], v148, off
